# grid sync after phase 0 now goes through the kernel's XCD-hierarchical barrier instead of the cooperative-groups counter barrier
# speedup vs baseline: 1.0107x; 1.0107x over previous
.LBB0_32:
	s_or_b64 exec, exec, s[4:5]
	v_lshrrev_b32_e32 v2, 20, v0
	v_lshrrev_b32_e32 v0, 10, v0
	v_or_b32_e32 v0, v0, v2
	s_movk_i32 s0, 0x3ff
	v_and_or_b32 v0, v0, s0, v188
	v_cmp_eq_u32_e32 vcc, 0, v0
	s_barrier
	s_barrier
	s_and_saveexec_b64 s[0:1], vcc
	s_xor_b64 s[0:1], exec, s[0:1]
	v_writelane_b32 v248, s24, 62
	s_nop 1
	v_writelane_b32 v248, s25, 63
	s_branch .LBB0_42
	buffer_wbl2 sc1
	s_waitcnt vmcnt(0)
	s_load_dwordx2 s[4:5], s[10:11], 0x58
	v_mov_b32_e32 v3, 0
	s_mov_b64 s[6:7], exec
	v_mbcnt_lo_u32_b32 v2, s6, 0
	v_mbcnt_hi_u32_b32 v2, s7, v2
	s_waitcnt lgkmcnt(0)
	global_load_dword v0, v3, s[4:5] offset:40
	v_cmp_eq_u32_e32 vcc, 0, v2
	s_and_saveexec_b64 s[10:11], vcc
	s_cbranch_execz .LBB0_35
	s_bcnt1_i32_b64 s6, s[6:7]
	v_mov_b32_e32 v4, s6
	global_atomic_add v4, v3, v4, s[4:5] offset:32 sc0

.LBB0_42:
	s_or_b64 exec, exec, s[0:1]
	s_add_u32 s34, s90, 0x9000000
	s_addc_u32 s35, s91, 0
	s_add_u32 s0, s90, 0x6500000
	s_addc_u32 s1, s91, 0
	v_writelane_b32 v249, s0, 17
	s_add_u32 s4, s90, 0x6400000
	s_addc_u32 s5, s91, 0
	v_writelane_b32 v249, s1, 18
	v_writelane_b32 v249, s4, 19
	s_mul_i32 s0, s95, s94
	s_mul_i32 s19, s0, s20
	v_writelane_b32 v249, s5, 20
	s_add_u32 s4, s90, 0x2000000
	s_addc_u32 s5, s91, 0
	v_writelane_b32 v249, s4, 21
	v_mov_b32_e32 v97, 0
	v_mov_b32_e32 v189, 0x358637bd
	v_writelane_b32 v249, s5, 22
	s_add_u32 s4, s90, 0x1d000000
	s_addc_u32 s5, s91, 0
	v_writelane_b32 v249, s4, 23
	v_mov_b32_e32 v190, 1
	v_mov_b32_e32 v191, 0x630
	v_writelane_b32 v249, s5, 24
	s_add_u32 s4, s90, 0x5400000
	s_addc_u32 s5, s91, 0
	v_writelane_b32 v249, s4, 25
	v_mov_b32_e32 v192, 0xc60
	v_mov_b32_e32 v193, 0x1290
	v_writelane_b32 v249, s5, 26
	s_add_u32 s4, s90, 0x4c00000
	s_addc_u32 s5, s91, 0
	s_add_u32 s48, s90, 0xd000000
	v_writelane_b32 v249, s4, 27
	s_addc_u32 s49, s91, 0
	v_mov_b32_e32 v194, 0x18c0
	v_writelane_b32 v249, s5, 28
	s_add_u32 s4, s90, 0x4400000
	s_addc_u32 s5, s91, 0
	v_writelane_b32 v249, s4, 29
	v_mov_b32_e32 v195, 0x4400
	v_mbcnt_hi_u32_b32 v196, -1, v1
	v_writelane_b32 v249, s5, 30
	s_add_u32 s4, s90, 0x2c00000
	s_addc_u32 s5, s91, 0
	v_writelane_b32 v249, s4, 31
	v_mov_b64_e32 v[178:179], 0x80000
	v_mov_b64_e32 v[180:181], 0x90000
	v_writelane_b32 v249, s5, 32
	s_add_u32 s4, s90, 0x19000000
	s_addc_u32 s5, s91, 0
	v_writelane_b32 v249, s4, 33
	v_mov_b64_e32 v[182:183], 0xa0000
	v_mov_b64_e32 v[184:185], 0xb0000
	v_writelane_b32 v249, s5, 34
	s_add_u32 s4, s90, 0x5c00000
	s_addc_u32 s5, s91, 0
	v_writelane_b32 v249, s4, 35
	s_cmpk_lt_i32 s94, 0x81
	v_mov_b32_e32 v197, 0xf149f2ca
	v_writelane_b32 v249, s5, 36
	s_cselect_b64 s[4:5], -1, 0
	v_writelane_b32 v249, s4, 37
	s_add_u32 s50, s90, 0x6d00000
	s_addc_u32 s51, s91, 0
	v_writelane_b32 v249, s5, 38
	s_mov_b32 s33, 0xffff0000
	v_readlane_b32 s2, v249, 16
	s_cmpk_gt_i32 s2, 0x7f
	s_cselect_b64 s[4:5], -1, 0
	s_add_i32 s1, s52, 0xfffffc00
	s_add_i32 s55, s56, 0xfffffc00
	v_writelane_b32 v249, s4, 39
	s_cmpk_lt_i32 s2, 0x80
	s_mov_b32 s97, 0x42b504f3
	v_writelane_b32 v249, s5, 40
	s_cselect_b64 s[4:5], -1, 0
	s_add_u32 s76, s90, 0x11000000
	s_addc_u32 s77, s91, 0
	s_add_u32 s60, s90, 0x15000000
	s_addc_u32 s61, s91, 0
	s_add_u32 s62, s90, 0x8f00200
	s_addc_u32 s63, s91, 0
	s_add_u32 s64, s90, 0x8f00400
	s_addc_u32 s65, s91, 0
	s_add_u32 s68, s90, 0x8f00500
	s_addc_u32 s69, s91, 0
	s_add_u32 s70, s90, 0x8f00600
	s_addc_u32 s71, s91, 0
	s_add_u32 s36, s90, 0x8f00700
	v_writelane_b32 v249, s1, 41
	s_addc_u32 s37, s91, 0
	v_writelane_b32 v249, s4, 42
	s_add_u32 s0, s90, 0x8f00800
	s_addc_u32 s1, s91, 0
	v_writelane_b32 v249, s5, 43
	v_writelane_b32 v249, s0, 44
	s_mov_b32 s96, 0
	s_mov_b64 s[20:21], 0x80
	v_writelane_b32 v249, s1, 45
	s_add_u32 s0, s90, 0x8f00900
	s_addc_u32 s1, s91, 0
	v_writelane_b32 v249, s0, 46
	s_mov_b32 s22, 0x3e0293ee
	s_mov_b64 s[30:31], 0x20000
	v_writelane_b32 v249, s1, 47
	s_add_u32 s0, s90, 0x8f00a00
	s_addc_u32 s1, s91, 0
	v_writelane_b32 v249, s0, 48
	s_barrier
	s_nop 0
	v_writelane_b32 v249, s1, 49
	s_add_u32 s0, s90, 0x8f00b00
	s_addc_u32 s1, s91, 0
	v_writelane_b32 v249, s0, 50
	s_nop 1
	v_writelane_b32 v249, s1, 51
	s_add_u32 s0, s90, 0x8f00c00
	s_addc_u32 s1, s91, 0
	v_writelane_b32 v249, s0, 52
	s_nop 1
	v_writelane_b32 v249, s1, 53
	s_add_u32 s0, s90, 0x8f00d00
	s_addc_u32 s1, s91, 0
	v_writelane_b32 v249, s0, 54
	s_nop 1
	v_writelane_b32 v249, s1, 55
	s_add_u32 s0, s90, 0x8f00e00
	s_addc_u32 s1, s91, 0
	v_writelane_b32 v249, s0, 56
	s_nop 1
	v_writelane_b32 v249, s1, 57
	s_add_u32 s0, s90, 0x8f00f00
	s_addc_u32 s1, s91, 0
	v_writelane_b32 v249, s0, 58
	s_nop 1
	v_writelane_b32 v249, s1, 59
	s_add_u32 s0, s90, 0x8f01000
	s_addc_u32 s1, s91, 0
	v_writelane_b32 v249, s0, 60
	s_nop 1
	v_writelane_b32 v249, s1, 61
	s_add_u32 s0, s90, 0x8f01100
	s_addc_u32 s1, s91, 0
	v_writelane_b32 v249, s0, 62
	s_nop 1
	v_writelane_b32 v249, s1, 63
	s_add_u32 s0, s90, 0x8f01200
	s_addc_u32 s1, s91, 0
	v_writelane_b32 v247, s0, 0
	s_nop 1
	v_writelane_b32 v247, s1, 1
	s_add_u32 s0, s90, 0x8f01300
	s_addc_u32 s1, s91, 0
	v_writelane_b32 v247, s0, 2
	s_cmp_eq_u32 s3, 15
	s_nop 0
	v_writelane_b32 v247, s1, 3
	s_cselect_b64 s[0:1], -1, 0
	v_writelane_b32 v247, s0, 4
	s_cmp_eq_u32 s3, 14
	s_nop 0
	v_writelane_b32 v247, s1, 5
	s_cselect_b64 s[0:1], -1, 0
	v_writelane_b32 v247, s0, 6
	s_cmp_eq_u32 s3, 13
	s_nop 0
	v_writelane_b32 v247, s1, 7
	s_cselect_b64 s[0:1], -1, 0
	v_writelane_b32 v247, s0, 8
	s_cmp_eq_u32 s3, 12
	s_nop 0
	v_writelane_b32 v247, s1, 9
	s_cselect_b64 s[0:1], -1, 0
	v_writelane_b32 v247, s0, 10
	s_cmp_eq_u32 s3, 11
	s_nop 0
	v_writelane_b32 v247, s1, 11
	s_cselect_b64 s[0:1], -1, 0
	v_writelane_b32 v247, s0, 12
	s_cmp_eq_u32 s3, 10
	s_nop 0
	v_writelane_b32 v247, s1, 13
	s_cselect_b64 s[0:1], -1, 0
	v_writelane_b32 v247, s0, 14
	s_cmp_eq_u32 s3, 9
	s_nop 0
	v_writelane_b32 v247, s1, 15
	s_cselect_b64 s[0:1], -1, 0
	v_writelane_b32 v247, s0, 16
	s_cmp_eq_u32 s3, 8
	s_nop 0
	v_writelane_b32 v247, s1, 17
	s_cselect_b64 s[0:1], -1, 0
	v_writelane_b32 v247, s0, 18
	s_cmp_eq_u32 s3, 7
	s_nop 0
	v_writelane_b32 v247, s1, 19
	s_cselect_b64 s[0:1], -1, 0
	v_writelane_b32 v247, s0, 20
	s_cmp_eq_u32 s3, 6
	s_nop 0
	v_writelane_b32 v247, s1, 21
	s_cselect_b64 s[0:1], -1, 0
	v_writelane_b32 v247, s0, 22
	s_cmp_eq_u32 s3, 5
	s_nop 0
	v_writelane_b32 v247, s1, 23
	s_cselect_b64 s[0:1], -1, 0
	v_writelane_b32 v247, s0, 24
	s_cmp_eq_u32 s3, 4
	s_nop 0
	v_writelane_b32 v247, s1, 25
	s_cselect_b64 s[0:1], -1, 0
	v_writelane_b32 v247, s0, 26
	s_cmp_eq_u32 s3, 3
	s_nop 0
	v_writelane_b32 v247, s1, 27
	s_cselect_b64 s[0:1], -1, 0
	v_writelane_b32 v247, s0, 28
	s_cmp_eq_u32 s3, 2
	s_nop 0
	v_writelane_b32 v247, s1, 29
	s_cselect_b64 s[0:1], -1, 0
	v_writelane_b32 v247, s0, 30
	s_cmp_eq_u32 s3, 1
	s_nop 0
	v_writelane_b32 v247, s1, 31
	s_cselect_b64 s[0:1], -1, 0
	v_writelane_b32 v247, s0, 32
	s_cmp_eq_u32 s3, 0
	s_nop 0
	v_writelane_b32 v247, s1, 33
	s_cselect_b64 s[0:1], -1, 0
	v_writelane_b32 v247, s0, 34
	s_nop 1
	v_writelane_b32 v247, s1, 35
	s_lshl_b32 s0, s3, 8
	s_add_u32 s0, s8, s0
	s_addc_u32 s1, s9, 0
	s_add_u32 s4, s0, 0x1400
	s_addc_u32 s5, s1, 0
	v_writelane_b32 v247, s4, 36
	s_add_u32 s0, s0, 0x2400
	s_addc_u32 s1, s1, 0
	v_writelane_b32 v247, s5, 37
	v_writelane_b32 v247, s0, 38
	s_nop 1
	v_writelane_b32 v247, s1, 39
	s_add_u32 s0, s90, 0x8f03400
	s_addc_u32 s1, s91, 0
	v_writelane_b32 v247, s0, 40
	s_nop 1
	v_writelane_b32 v247, s1, 41
	s_add_u32 s0, s90, 0x8f03500
	s_addc_u32 s1, s91, 0
	v_writelane_b32 v247, s0, 42
	s_ashr_i32 s95, s94, 31
	s_nop 0
	v_writelane_b32 v247, s1, 43
	s_ashr_i32 s0, s2, 31
	v_writelane_b32 v247, s0, 44
	s_lshr_b32 s0, s0, 29
	s_add_i32 s0, s2, s0
	s_ashr_i32 s1, s0, 3
	s_and_b32 s0, s0, -8
	v_writelane_b32 v247, s1, 45
	s_sub_i32 s1, s2, s0
	s_add_u32 s4, s90, 0x8e10000
	s_addc_u32 s5, s91, 0
	v_writelane_b32 v247, s4, 46
	s_nop 1
	v_writelane_b32 v247, s5, 47
	s_add_u32 s4, s90, 0x8e20000
	s_addc_u32 s5, s91, 0
	s_add_u32 s67, s90, 0x7d00000
	s_addc_u32 s72, s91, 0
	v_writelane_b32 v247, s4, 48
	s_cmpk_lt_i32 s2, 0x400
	s_nop 0
	v_writelane_b32 v247, s5, 49
	s_cselect_b64 s[4:5], -1, 0
	v_writelane_b32 v247, s4, 50
	s_lshl_b32 s0, s2, 12
	s_add_i32 s0, s0, 0xfff7f800
	v_writelane_b32 v247, s5, 51
	v_writelane_b32 v247, s0, 52
	v_writelane_b32 v247, s1, 53
	s_lshr_b32 s0, s1, 31
	v_writelane_b32 v247, s0, 54
	s_lshl_b32 s1, s94, 12
	v_writelane_b32 v247, s1, 55
	s_add_i32 s1, s1, 0xfff80000
	s_lshl_b32 s0, s2, 5
	v_writelane_b32 v247, s1, 56
	v_writelane_b32 v247, s0, 57
	s_addk_i32 s0, 0xf000
	s_lshl_b32 s2, s94, 5
	v_writelane_b32 v247, s0, 58
	v_writelane_b32 v247, s2, 59
	s_add_i32 s0, s2, 0xfffff000
	v_writelane_b32 v247, s0, 60
	s_add_u32 s0, s90, 0x7d48000
	s_addc_u32 s1, s91, 0
	v_writelane_b32 v247, s0, 61
	s_ashr_i32 s57, s56, 31
	s_add_i32 s73, 0, 0xf400
	v_writelane_b32 v247, s1, 62
	s_add_i32 s0, 0, 0x8800
	v_writelane_b32 v247, s0, 63
	s_add_i32 s0, 0, 0x100
	v_writelane_b32 v248, s0, 0
	s_add_i32 s0, 0, 0x18400
	v_writelane_b32 v248, s0, 1
	s_add_i32 s0, 0, 0x1cc00
	v_writelane_b32 v248, s0, 2
	s_add_i32 s0, 0, 0x20020
	v_writelane_b32 v248, s0, 3
	s_add_i32 s0, 0, 0x20024
	v_writelane_b32 v248, s0, 4
	s_lshl_b64 s[0:1], s[56:57], 12
	v_writelane_b32 v248, s0, 5
	s_mov_b32 s2, 0x800000
	s_mov_b32 s5, 0
	v_writelane_b32 v248, s1, 6
	s_mov_b32 s0, s94
	v_writelane_b32 v248, s0, 7
	s_nop 1
	v_writelane_b32 v248, s1, 8
	v_writelane_b32 v248, s60, 9
	s_nop 1
	v_writelane_b32 v248, s61, 10
	v_writelane_b32 v248, s19, 11
	v_writelane_b32 v248, s62, 12
	s_nop 1
	v_writelane_b32 v248, s63, 13
	v_writelane_b32 v248, s64, 14
	s_nop 1
	v_writelane_b32 v248, s65, 15
	v_writelane_b32 v248, s68, 16
	s_nop 1
	v_writelane_b32 v248, s69, 17
	v_writelane_b32 v248, s70, 18
	s_nop 1
	v_writelane_b32 v248, s71, 19
	v_writelane_b32 v248, s36, 20
	s_nop 1
	v_writelane_b32 v248, s37, 21
	v_writelane_b32 v248, s95, 22
	v_writelane_b32 v248, s67, 23
	v_writelane_b32 v248, s72, 24
	v_writelane_b32 v248, s73, 25
	v_writelane_b32 v248, s58, 26
	s_nop 1
	v_writelane_b32 v248, s59, 27
	v_writelane_b32 v248, s52, 28
	v_writelane_b32 v248, s84, 29
	s_nop 1
	v_writelane_b32 v248, s85, 30
	v_writelane_b32 v248, s86, 31
	v_writelane_b32 v248, s87, 32
	v_writelane_b32 v248, s88, 33
	v_writelane_b32 v248, s89, 34
	v_writelane_b32 v248, s90, 35
	v_writelane_b32 v248, s91, 36
	v_writelane_b32 v248, s48, 37
	s_nop 1
	v_writelane_b32 v248, s49, 38
	v_writelane_b32 v248, s50, 39
	s_nop 1
	v_writelane_b32 v248, s51, 40
	v_writelane_b32 v248, s55, 41
	v_writelane_b32 v248, s76, 42
	s_nop 1
	v_writelane_b32 v248, s77, 43
	s_mov_b32 s96, -1
	s_mov_b64 s[0:1], -1
	v_writelane_b32 v246, s0, 0
	s_nop 1
	v_writelane_b32 v246, s1, 1
	s_branch .LBB0_582
